# P5 epilogue: row statistics computed up front from quarter loads + bpermute, rotary rows prefetched 3 groups ahead, counted waits
# speedup vs baseline: 1.0149x; 1.0149x over previous
.LBB5_637:
	v_lshl_add_u32 v180, s4, 8, v182
	v_ashrrev_i32_e32 v181, 31, v180
	v_lshlrev_b64 v[32:33], 6, v[180:181]
	v_lshl_add_u64 v[32:33], s[36:37], 0, v[32:33]
	s_cmp_eq_u32 s3, 2
	s_cselect_b64 s[6:7], -1, 0
	s_or_b64 s[4:5], s[8:9], s[6:7]
	s_and_b64 s[8:9], s[44:45], s[4:5]
	v_cndmask_b32_e64 v32, 0, 1, s[8:9]
	v_cmp_ne_u32_e64 s[4:5], 1, v32
	s_andn2_b64 vcc, exec, s[8:9]
	s_cbranch_vccnz .LBB5_639
	v_lshlrev_b32_e32 v191, 5, v180
	v_and_b32_e32 v191, 0x3ffe0, v191
	v_add_u32_e32 v255, 0x1000, v191
	global_load_dwordx4 v[32:35], v191, s[38:39] offset:16
	global_load_dwordx4 v[36:39], v191, s[38:39]
	global_load_dwordx4 v[40:43], v191, s[40:41] offset:16
	global_load_dwordx4 v[44:47], v191, s[40:41]
	global_load_dwordx4 v[192:195], v191, s[38:39] offset:528
	global_load_dwordx4 v[196:199], v191, s[38:39] offset:512
	global_load_dwordx4 v[200:203], v191, s[40:41] offset:528
	global_load_dwordx4 v[204:207], v191, s[40:41] offset:512
	global_load_dwordx4 v[208:211], v191, s[38:39] offset:1040
	global_load_dwordx4 v[212:215], v191, s[38:39] offset:1024
	global_load_dwordx4 v[216:219], v191, s[40:41] offset:1040
	global_load_dwordx4 v[220:223], v191, s[40:41] offset:1024
.LBB5_639:
	v_mbcnt_lo_u32_b32 v248, -1, 0
	v_mbcnt_hi_u32_b32 v248, -1, v248
	v_and_b32_e32 v251, 15, v248
	v_lshlrev_b32_e32 v251, 2, v251
	v_add_u32_e32 v252, 64, v251
	v_add_u32_e32 v253, 0x80, v251
	v_add_u32_e32 v254, 0xc0, v251
	v_lshrrev_b32_e32 v248, 4, v248
	v_lshlrev_b32_e32 v248, 4, v248
	v_lshl_add_u32 v248, v180, 6, v248
	v_add_u32_e32 v249, 0x2000, v248
	global_load_dwordx4 v[144:147], v248, s[36:37]
	global_load_dwordx4 v[148:151], v248, s[36:37] offset:1024
	global_load_dwordx4 v[152:155], v248, s[36:37] offset:2048
	global_load_dwordx4 v[156:159], v248, s[36:37] offset:3072
	global_load_dwordx4 v[224:227], v249, s[36:37]
	global_load_dwordx4 v[228:231], v249, s[36:37] offset:1024
	global_load_dwordx4 v[232:235], v249, s[36:37] offset:2048
	global_load_dwordx4 v[236:239], v249, s[36:37] offset:3072
	s_waitcnt vmcnt(0)
	v_add_f32_e32 v144, v144, v145
	v_add_f32_e32 v146, v146, v147
	v_add_f32_e32 v148, v148, v149
	v_add_f32_e32 v150, v150, v151
	v_add_f32_e32 v152, v152, v153
	v_add_f32_e32 v154, v154, v155
	v_add_f32_e32 v156, v156, v157
	v_add_f32_e32 v158, v158, v159
	v_add_f32_e32 v224, v224, v225
	v_add_f32_e32 v226, v226, v227
	v_add_f32_e32 v228, v228, v229
	v_add_f32_e32 v230, v230, v231
	v_add_f32_e32 v232, v232, v233
	v_add_f32_e32 v234, v234, v235
	v_add_f32_e32 v236, v236, v237
	v_add_f32_e32 v238, v238, v239
	v_add_f32_e32 v144, v144, v146
	v_add_f32_e32 v148, v148, v150
	v_add_f32_e32 v152, v152, v154
	v_add_f32_e32 v156, v156, v158
	v_add_f32_e32 v224, v224, v226
	v_add_f32_e32 v228, v228, v230
	v_add_f32_e32 v232, v232, v234
	v_add_f32_e32 v236, v236, v238
	ds_bpermute_b32 v240, v251, v144
	ds_bpermute_b32 v145, v252, v144
	ds_bpermute_b32 v146, v253, v144
	ds_bpermute_b32 v147, v254, v144
	ds_bpermute_b32 v241, v251, v148
	ds_bpermute_b32 v149, v252, v148
	ds_bpermute_b32 v150, v253, v148
	ds_bpermute_b32 v151, v254, v148
	ds_bpermute_b32 v242, v251, v152
	ds_bpermute_b32 v153, v252, v152
	ds_bpermute_b32 v154, v253, v152
	ds_bpermute_b32 v155, v254, v152
	ds_bpermute_b32 v243, v251, v156
	ds_bpermute_b32 v157, v252, v156
	ds_bpermute_b32 v158, v253, v156
	ds_bpermute_b32 v159, v254, v156
	ds_bpermute_b32 v244, v251, v224
	ds_bpermute_b32 v225, v252, v224
	ds_bpermute_b32 v226, v253, v224
	ds_bpermute_b32 v227, v254, v224
	ds_bpermute_b32 v245, v251, v228
	ds_bpermute_b32 v229, v252, v228
	ds_bpermute_b32 v230, v253, v228
	ds_bpermute_b32 v231, v254, v228
	ds_bpermute_b32 v246, v251, v232
	ds_bpermute_b32 v233, v252, v232
	ds_bpermute_b32 v234, v253, v232
	ds_bpermute_b32 v235, v254, v232
	ds_bpermute_b32 v247, v251, v236
	ds_bpermute_b32 v237, v252, v236
	ds_bpermute_b32 v238, v253, v236
	ds_bpermute_b32 v239, v254, v236
	s_waitcnt lgkmcnt(0)
	v_add_f32_e32 v240, v240, v145
	v_add_f32_e32 v241, v241, v149
	v_add_f32_e32 v242, v242, v153
	v_add_f32_e32 v243, v243, v157
	v_add_f32_e32 v244, v244, v225
	v_add_f32_e32 v245, v245, v229
	v_add_f32_e32 v246, v246, v233
	v_add_f32_e32 v247, v247, v237
	v_add_f32_e32 v240, v240, v146
	v_add_f32_e32 v241, v241, v150
	v_add_f32_e32 v242, v242, v154
	v_add_f32_e32 v243, v243, v158
	v_add_f32_e32 v244, v244, v226
	v_add_f32_e32 v245, v245, v230
	v_add_f32_e32 v246, v246, v234
	v_add_f32_e32 v247, v247, v238
	v_add_f32_e32 v240, v240, v147
	v_add_f32_e32 v241, v241, v151
	v_add_f32_e32 v242, v242, v155
	v_add_f32_e32 v243, v243, v159
	v_add_f32_e32 v244, v244, v227
	v_add_f32_e32 v245, v245, v231
	v_add_f32_e32 v246, v246, v235
	v_add_f32_e32 v247, v247, v239
	v_fmamk_f32 v144, v240, 0x3a800000, v189
	v_mul_f32_e32 v145, 0x4f800000, v144
	v_cmp_gt_f32_e32 vcc, s82, v144
	s_nop 1
	v_cndmask_b32_e32 v144, v144, v145, vcc
	v_sqrt_f32_e32 v145, v144
	s_nop 0
	v_add_u32_e32 v146, -1, v145
	v_fma_f32 v147, -v146, v145, v144
	v_cmp_ge_f32_e64 s[8:9], 0, v147
	v_add_u32_e32 v147, 1, v145
	s_nop 0
	v_cndmask_b32_e64 v146, v145, v146, s[8:9]
	v_fma_f32 v145, -v147, v145, v144
	v_cmp_lt_f32_e64 s[8:9], 0, v145
	s_nop 1
	v_cndmask_b32_e64 v145, v146, v147, s[8:9]
	v_mul_f32_e32 v146, 0x37800000, v145
	v_cndmask_b32_e32 v145, v145, v146, vcc
	v_cmp_class_f32_e32 vcc, v144, v190
	s_nop 1
	v_cndmask_b32_e32 v144, v145, v144, vcc
	v_div_scale_f32 v145, s[8:9], v144, v144, 1.0
	v_rcp_f32_e32 v146, v145
	s_nop 0
	v_fma_f32 v147, -v145, v146, 1.0
	v_fmac_f32_e32 v146, v147, v146
	v_div_scale_f32 v147, vcc, 1.0, v144, 1.0
	v_mul_f32_e32 v148, v147, v146
	v_fma_f32 v149, -v145, v148, v147
	v_fmac_f32_e32 v148, v149, v146
	v_fma_f32 v145, -v145, v148, v147
	v_div_fmas_f32 v145, v145, v146, v148
	v_div_fixup_f32 v144, v145, v144, 1.0
	v_mul_f32_e32 v145, 0x3e38aa3b, v144
	v_cndmask_b32_e64 v146, v144, v145, s[6:7]
	v_pk_mul_f32 v[142:143], v[142:143], v[146:147] op_sel_hi:[1,0]
	v_pk_mul_f32 v[140:141], v[140:141], v[146:147] op_sel_hi:[1,0]
	v_pk_mul_f32 v[138:139], v[138:139], v[146:147] op_sel_hi:[1,0]
	s_and_b64 vcc, exec, s[4:5]
	v_pk_mul_f32 v[148:149], v[136:137], v[146:147] op_sel_hi:[1,0]
	s_cbranch_vccnz .LBB5_643
	ds_bpermute_b32 v144, v185, v140
	ds_bpermute_b32 v136, v185, v148
	ds_bpermute_b32 v145, v185, v141
	ds_bpermute_b32 v137, v185, v149
	ds_bpermute_b32 v152, v185, v142
	ds_bpermute_b32 v151, v185, v138
	ds_bpermute_b32 v150, v185, v143
	ds_bpermute_b32 v147, v185, v139
	s_and_saveexec_b64 s[8:9], s[0:1]
	s_cbranch_execz .LBB5_642
	s_waitcnt lgkmcnt(2)
	v_mul_f32_e32 v151, v170, v151
	v_mul_f32_e32 v154, v42, v151
	s_waitcnt lgkmcnt(1)
	v_mul_f32_e32 v151, v170, v150
	v_mov_b32_e32 v156, v143
	v_mov_b32_e32 v157, v47
	v_mov_b32_e32 v150, v39
	v_pk_mul_f32 v[140:141], v[140:141], v[36:37]
	v_pk_mul_f32 v[144:145], v[170:171], v[144:145]
	v_pk_mul_f32 v[150:151], v[156:157], v[150:151]
	v_pk_fma_f32 v[140:141], v[44:45], v[144:145], v[140:141]
	v_mov_b32_e32 v143, v150
	v_mov_b32_e32 v153, v151
	s_waitcnt lgkmcnt(0)
	v_mul_f32_e32 v145, v170, v147
	v_mov_b32_e32 v150, v139
	v_mov_b32_e32 v151, v43
	v_mov_b32_e32 v144, v35
	v_mul_f32_e32 v152, v170, v152
	v_pk_mul_f32 v[144:145], v[150:151], v[144:145]
	v_pk_mul_f32 v[148:149], v[148:149], v[32:33]
	v_pk_mul_f32 v[136:137], v[170:171], v[136:137]
	v_mul_f32_e32 v142, v142, v38
	v_mul_f32_e32 v152, v46, v152
	v_mul_f32_e32 v138, v138, v34
	v_mov_b32_e32 v139, v144
	v_mov_b32_e32 v155, v145
	v_pk_add_f32 v[142:143], v[142:143], v[152:153]
	v_pk_fma_f32 v[148:149], v[40:41], v[136:137], v[148:149]
	v_pk_add_f32 v[138:139], v[138:139], v[154:155]

.LBB5_651:
	s_waitcnt lgkmcnt(2)
	v_or_b32_e32 v146, 16, v180
	v_ashrrev_i32_e32 v147, 31, v146
	v_cvt_pk_bf16_f32 v132, v132, v133
	v_cvt_pk_bf16_f32 v133, v134, v135
	v_cvt_pk_bf16_f32 v134, v128, v129
	v_lshlrev_b64 v[128:129], 6, v[146:147]
	v_cvt_pk_bf16_f32 v135, v130, v131
	global_store_dwordx4 v[136:137], v[132:135], off offset:256
	v_lshl_add_u64 v[140:141], s[36:37], 0, v[128:129]
	s_waitcnt lgkmcnt(0)
	s_and_b64 vcc, exec, s[4:5]
	s_cbranch_vccnz .LBB5_653
	global_load_dwordx4 v[32:35], v191, s[38:39] offset:1552
	global_load_dwordx4 v[36:39], v191, s[38:39] offset:1536
	global_load_dwordx4 v[40:43], v191, s[40:41] offset:1552
	global_load_dwordx4 v[44:47], v191, s[40:41] offset:1536
.LBB5_653:
	v_fmamk_f32 v128, v241, 0x3a800000, v189
	v_mul_f32_e32 v129, 0x4f800000, v128
	v_cmp_gt_f32_e32 vcc, s82, v128
	s_nop 1
	v_cndmask_b32_e32 v128, v128, v129, vcc
	v_sqrt_f32_e32 v129, v128
	s_nop 0
	v_add_u32_e32 v130, -1, v129
	v_fma_f32 v131, -v130, v129, v128
	v_cmp_ge_f32_e64 s[12:13], 0, v131
	v_add_u32_e32 v131, 1, v129
	s_nop 0
	v_cndmask_b32_e64 v130, v129, v130, s[12:13]
	v_fma_f32 v129, -v131, v129, v128
	v_cmp_lt_f32_e64 s[12:13], 0, v129
	s_nop 1
	v_cndmask_b32_e64 v129, v130, v131, s[12:13]
	v_mul_f32_e32 v130, 0x37800000, v129
	v_cndmask_b32_e32 v129, v129, v130, vcc
	v_cmp_class_f32_e32 vcc, v128, v190
	s_nop 1
	v_cndmask_b32_e32 v128, v129, v128, vcc
	v_div_scale_f32 v129, s[12:13], v128, v128, 1.0
	v_rcp_f32_e32 v130, v129
	s_nop 0
	v_fma_f32 v131, -v129, v130, 1.0
	v_fmac_f32_e32 v130, v131, v130
	v_div_scale_f32 v131, vcc, 1.0, v128, 1.0
	v_mul_f32_e32 v132, v131, v130
	v_fma_f32 v133, -v129, v132, v131
	v_fmac_f32_e32 v132, v133, v130
	v_fma_f32 v129, -v129, v132, v131
	v_div_fmas_f32 v129, v129, v130, v132
	v_div_fixup_f32 v128, v129, v128, 1.0
	v_mul_f32_e32 v129, 0x3e38aa3b, v128
	v_cndmask_b32_e64 v128, v128, v129, s[6:7]
	v_pk_mul_f32 v[126:127], v[126:127], v[128:129] op_sel_hi:[1,0]
	v_pk_mul_f32 v[124:125], v[124:125], v[128:129] op_sel_hi:[1,0]
	v_pk_mul_f32 v[122:123], v[122:123], v[128:129] op_sel_hi:[1,0]
	s_and_b64 vcc, exec, s[4:5]
	v_pk_mul_f32 v[130:131], v[120:121], v[128:129] op_sel_hi:[1,0]
	s_cbranch_vccnz .LBB5_657
	ds_bpermute_b32 v132, v185, v124
	ds_bpermute_b32 v120, v185, v130
	ds_bpermute_b32 v133, v185, v125
	ds_bpermute_b32 v121, v185, v131
	ds_bpermute_b32 v136, v185, v126
	ds_bpermute_b32 v135, v185, v122
	ds_bpermute_b32 v134, v185, v127
	ds_bpermute_b32 v129, v185, v123
	s_and_saveexec_b64 s[12:13], s[0:1]
	s_cbranch_execz .LBB5_656
	s_waitcnt lgkmcnt(2)
	v_mul_f32_e32 v135, v170, v135
	v_mul_f32_e32 v138, v202, v135
	s_waitcnt lgkmcnt(1)
	v_mul_f32_e32 v135, v170, v134
	v_mov_b32_e32 v140, v127
	v_mov_b32_e32 v141, v207
	v_mov_b32_e32 v134, v199
	v_pk_mul_f32 v[124:125], v[124:125], v[196:197]
	v_pk_mul_f32 v[132:133], v[170:171], v[132:133]
	v_pk_mul_f32 v[134:135], v[140:141], v[134:135]
	v_pk_fma_f32 v[124:125], v[204:205], v[132:133], v[124:125]
	v_mov_b32_e32 v127, v134
	v_mov_b32_e32 v137, v135
	s_waitcnt lgkmcnt(0)
	v_mul_f32_e32 v133, v170, v129
	v_mov_b32_e32 v134, v123
	v_mov_b32_e32 v135, v203
	v_mov_b32_e32 v132, v195
	v_mul_f32_e32 v136, v170, v136
	v_pk_mul_f32 v[132:133], v[134:135], v[132:133]
	v_pk_mul_f32 v[130:131], v[130:131], v[192:193]
	v_pk_mul_f32 v[120:121], v[170:171], v[120:121]
	v_mul_f32_e32 v126, v126, v198
	v_mul_f32_e32 v136, v206, v136
	v_mul_f32_e32 v122, v122, v194
	v_mov_b32_e32 v123, v132
	v_mov_b32_e32 v139, v133
	v_pk_add_f32 v[126:127], v[126:127], v[136:137]
	v_pk_fma_f32 v[130:131], v[200:201], v[120:121], v[130:131]
	v_pk_add_f32 v[122:123], v[122:123], v[138:139]

.LBB5_659:
	s_waitcnt lgkmcnt(0)
	v_mov_b32_e32 v129, v128
	v_lshlrev_b64 v[120:121], 11, v[146:147]
	v_cvt_pk_bf16_f32 v124, v124, v125
	v_cvt_pk_bf16_f32 v125, v126, v127
	v_cvt_pk_bf16_f32 v126, v130, v131
	v_cvt_pk_bf16_f32 v127, v122, v123
	v_mov_b32_e32 v122, v128
	v_mov_b32_e32 v123, v128
	v_lshl_add_u64 v[120:121], v[144:145], 0, v[120:121]
	v_pk_mul_f32 v[118:119], v[118:119], v[122:123]
	v_pk_mul_f32 v[116:117], v[116:117], v[128:129]
	v_pk_mul_f32 v[114:115], v[114:115], v[122:123]
	s_and_b64 vcc, exec, s[4:5]
	v_pk_mul_f32 v[112:113], v[112:113], v[128:129]
	global_store_dwordx4 v[120:121], v[124:127], off
	s_cbranch_vccnz .LBB5_663
	ds_bpermute_b32 v124, v185, v116
	ds_bpermute_b32 v122, v185, v112
	ds_bpermute_b32 v125, v185, v117
	ds_bpermute_b32 v123, v185, v113
	ds_bpermute_b32 v129, v185, v118
	ds_bpermute_b32 v128, v185, v114
	ds_bpermute_b32 v127, v185, v119
	ds_bpermute_b32 v126, v185, v115
	s_and_saveexec_b64 s[12:13], s[0:1]
	s_cbranch_execz .LBB5_662
	v_pk_mul_f32 v[116:117], v[116:117], v[196:197]
	s_waitcnt lgkmcnt(5)
	v_pk_mul_f32 v[124:125], v[170:171], v[124:125]
	s_waitcnt lgkmcnt(1)
	v_mul_f32_e32 v133, v170, v127
	v_mov_b32_e32 v134, v119
	v_mov_b32_e32 v135, v207
	v_mov_b32_e32 v132, v199
	v_pk_fma_f32 v[116:117], v[204:205], v[124:125], v[116:117]
	s_waitcnt lgkmcnt(0)
	v_mul_f32_e32 v125, v170, v126
	v_mov_b32_e32 v126, v115
	v_mov_b32_e32 v127, v203
	v_mov_b32_e32 v124, v195
	v_mul_f32_e32 v129, v170, v129
	v_mul_f32_e32 v128, v170, v128
	v_pk_mul_f32 v[132:133], v[134:135], v[132:133]
	v_pk_mul_f32 v[124:125], v[126:127], v[124:125]
	v_pk_mul_f32 v[112:113], v[112:113], v[192:193]
	v_pk_mul_f32 v[122:123], v[170:171], v[122:123]
	v_mul_f32_e32 v118, v118, v198
	v_mul_f32_e32 v130, v206, v129
	v_mul_f32_e32 v114, v114, v194
	v_mul_f32_e32 v128, v202, v128
	v_mov_b32_e32 v119, v132
	v_mov_b32_e32 v131, v133
	v_mov_b32_e32 v115, v124
	v_mov_b32_e32 v129, v125
	v_pk_add_f32 v[118:119], v[118:119], v[130:131]
	v_pk_fma_f32 v[112:113], v[200:201], v[122:123], v[112:113]
	v_pk_add_f32 v[114:115], v[114:115], v[128:129]

.LBB5_665:
	s_waitcnt lgkmcnt(2)
	v_or_b32_e32 v128, 32, v180
	v_ashrrev_i32_e32 v129, 31, v128
	v_cvt_pk_bf16_f32 v116, v116, v117
	v_cvt_pk_bf16_f32 v117, v118, v119
	v_cvt_pk_bf16_f32 v118, v112, v113
	v_lshlrev_b64 v[112:113], 6, v[128:129]
	v_cvt_pk_bf16_f32 v119, v114, v115
	global_store_dwordx4 v[120:121], v[116:119], off offset:256
	v_lshl_add_u64 v[124:125], s[36:37], 0, v[112:113]
	s_waitcnt lgkmcnt(0)
	s_and_b64 vcc, exec, s[4:5]
	s_cbranch_vccnz .LBB5_667
	global_load_dwordx4 v[192:195], v255, s[38:39] offset:16
	global_load_dwordx4 v[196:199], v255, s[38:39]
	global_load_dwordx4 v[200:203], v255, s[40:41] offset:16
	global_load_dwordx4 v[204:207], v255, s[40:41]
.LBB5_667:
	v_fmamk_f32 v112, v242, 0x3a800000, v189
	v_mul_f32_e32 v113, 0x4f800000, v112
	v_cmp_gt_f32_e32 vcc, s82, v112
	s_nop 1
	v_cndmask_b32_e32 v112, v112, v113, vcc
	v_sqrt_f32_e32 v113, v112
	s_nop 0
	v_add_u32_e32 v114, -1, v113
	v_fma_f32 v115, -v114, v113, v112
	v_cmp_ge_f32_e64 s[12:13], 0, v115
	v_add_u32_e32 v115, 1, v113
	s_nop 0
	v_cndmask_b32_e64 v114, v113, v114, s[12:13]
	v_fma_f32 v113, -v115, v113, v112
	v_cmp_lt_f32_e64 s[12:13], 0, v113
	s_nop 1
	v_cndmask_b32_e64 v113, v114, v115, s[12:13]
	v_mul_f32_e32 v114, 0x37800000, v113
	v_cndmask_b32_e32 v113, v113, v114, vcc
	v_cmp_class_f32_e32 vcc, v112, v190
	s_nop 1
	v_cndmask_b32_e32 v112, v113, v112, vcc
	v_div_scale_f32 v113, s[12:13], v112, v112, 1.0
	v_rcp_f32_e32 v114, v113
	s_nop 0
	v_fma_f32 v115, -v113, v114, 1.0
	v_fmac_f32_e32 v114, v115, v114
	v_div_scale_f32 v115, vcc, 1.0, v112, 1.0
	v_mul_f32_e32 v116, v115, v114
	v_fma_f32 v117, -v113, v116, v115
	v_fmac_f32_e32 v116, v117, v114
	v_fma_f32 v113, -v113, v116, v115
	v_div_fmas_f32 v113, v113, v114, v116
	v_div_fixup_f32 v112, v113, v112, 1.0
	v_mul_f32_e32 v113, 0x3e38aa3b, v112
	v_cndmask_b32_e64 v112, v112, v113, s[6:7]
	v_pk_mul_f32 v[110:111], v[110:111], v[112:113] op_sel_hi:[1,0]
	v_pk_mul_f32 v[108:109], v[108:109], v[112:113] op_sel_hi:[1,0]
	v_pk_mul_f32 v[106:107], v[106:107], v[112:113] op_sel_hi:[1,0]
	s_and_b64 vcc, exec, s[4:5]
	v_pk_mul_f32 v[114:115], v[104:105], v[112:113] op_sel_hi:[1,0]
	s_cbranch_vccnz .LBB5_671
	ds_bpermute_b32 v116, v185, v108
	ds_bpermute_b32 v104, v185, v114
	ds_bpermute_b32 v117, v185, v109
	ds_bpermute_b32 v105, v185, v115
	ds_bpermute_b32 v120, v185, v110
	ds_bpermute_b32 v119, v185, v106
	ds_bpermute_b32 v118, v185, v111
	ds_bpermute_b32 v113, v185, v107
	s_and_saveexec_b64 s[12:13], s[0:1]
	s_cbranch_execz .LBB5_670
	s_waitcnt lgkmcnt(2)
	v_mul_f32_e32 v119, v170, v119
	v_mul_f32_e32 v122, v218, v119
	s_waitcnt lgkmcnt(1)
	v_mul_f32_e32 v119, v170, v118
	v_mov_b32_e32 v124, v111
	v_mov_b32_e32 v125, v223
	v_mov_b32_e32 v118, v215
	v_pk_mul_f32 v[108:109], v[108:109], v[212:213]
	v_pk_mul_f32 v[116:117], v[170:171], v[116:117]
	v_pk_mul_f32 v[118:119], v[124:125], v[118:119]
	v_pk_fma_f32 v[108:109], v[220:221], v[116:117], v[108:109]
	v_mov_b32_e32 v111, v118
	v_mov_b32_e32 v121, v119
	s_waitcnt lgkmcnt(0)
	v_mul_f32_e32 v117, v170, v113
	v_mov_b32_e32 v118, v107
	v_mov_b32_e32 v119, v219
	v_mov_b32_e32 v116, v211
	v_mul_f32_e32 v120, v170, v120
	v_pk_mul_f32 v[116:117], v[118:119], v[116:117]
	v_pk_mul_f32 v[114:115], v[114:115], v[208:209]
	v_pk_mul_f32 v[104:105], v[170:171], v[104:105]
	v_mul_f32_e32 v110, v110, v214
	v_mul_f32_e32 v120, v222, v120
	v_mul_f32_e32 v106, v106, v210
	v_mov_b32_e32 v107, v116
	v_mov_b32_e32 v123, v117
	v_pk_add_f32 v[110:111], v[110:111], v[120:121]
	v_pk_fma_f32 v[114:115], v[216:217], v[104:105], v[114:115]
	v_pk_add_f32 v[106:107], v[106:107], v[122:123]

.LBB5_673:
	s_waitcnt lgkmcnt(0)
	v_mov_b32_e32 v113, v112
	v_lshlrev_b64 v[104:105], 11, v[128:129]
	v_cvt_pk_bf16_f32 v108, v108, v109
	v_cvt_pk_bf16_f32 v109, v110, v111
	v_cvt_pk_bf16_f32 v110, v114, v115
	v_cvt_pk_bf16_f32 v111, v106, v107
	v_mov_b32_e32 v106, v112
	v_mov_b32_e32 v107, v112
	v_lshl_add_u64 v[104:105], v[144:145], 0, v[104:105]
	v_pk_mul_f32 v[102:103], v[102:103], v[106:107]
	v_pk_mul_f32 v[100:101], v[100:101], v[112:113]
	v_pk_mul_f32 v[98:99], v[98:99], v[106:107]
	s_and_b64 vcc, exec, s[4:5]
	v_pk_mul_f32 v[96:97], v[96:97], v[112:113]
	global_store_dwordx4 v[104:105], v[108:111], off
	s_cbranch_vccnz .LBB5_677
	ds_bpermute_b32 v108, v185, v100
	ds_bpermute_b32 v106, v185, v96
	ds_bpermute_b32 v109, v185, v101
	ds_bpermute_b32 v107, v185, v97
	ds_bpermute_b32 v113, v185, v102
	ds_bpermute_b32 v112, v185, v98
	ds_bpermute_b32 v111, v185, v103
	ds_bpermute_b32 v110, v185, v99
	s_and_saveexec_b64 s[12:13], s[0:1]
	s_cbranch_execz .LBB5_676
	v_pk_mul_f32 v[100:101], v[100:101], v[212:213]
	s_waitcnt lgkmcnt(5)
	v_pk_mul_f32 v[108:109], v[170:171], v[108:109]
	s_waitcnt lgkmcnt(1)
	v_mul_f32_e32 v117, v170, v111
	v_mov_b32_e32 v118, v103
	v_mov_b32_e32 v119, v223
	v_mov_b32_e32 v116, v215
	v_pk_fma_f32 v[100:101], v[220:221], v[108:109], v[100:101]
	s_waitcnt lgkmcnt(0)
	v_mul_f32_e32 v109, v170, v110
	v_mov_b32_e32 v110, v99
	v_mov_b32_e32 v111, v219
	v_mov_b32_e32 v108, v211
	v_mul_f32_e32 v113, v170, v113
	v_mul_f32_e32 v112, v170, v112
	v_pk_mul_f32 v[116:117], v[118:119], v[116:117]
	v_pk_mul_f32 v[108:109], v[110:111], v[108:109]
	v_pk_mul_f32 v[96:97], v[96:97], v[208:209]
	v_pk_mul_f32 v[106:107], v[170:171], v[106:107]
	v_mul_f32_e32 v102, v102, v214
	v_mul_f32_e32 v114, v222, v113
	v_mul_f32_e32 v98, v98, v210
	v_mul_f32_e32 v112, v218, v112
	v_mov_b32_e32 v103, v116
	v_mov_b32_e32 v115, v117
	v_mov_b32_e32 v99, v108
	v_mov_b32_e32 v113, v109
	v_pk_add_f32 v[102:103], v[102:103], v[114:115]
	v_pk_fma_f32 v[96:97], v[216:217], v[106:107], v[96:97]
	v_pk_add_f32 v[98:99], v[98:99], v[112:113]

.LBB5_679:
	s_waitcnt lgkmcnt(2)
	v_or_b32_e32 v112, 48, v180
	v_ashrrev_i32_e32 v113, 31, v112
	v_cvt_pk_bf16_f32 v100, v100, v101
	v_cvt_pk_bf16_f32 v101, v102, v103
	v_cvt_pk_bf16_f32 v102, v96, v97
	v_lshlrev_b64 v[96:97], 6, v[112:113]
	v_cvt_pk_bf16_f32 v103, v98, v99
	global_store_dwordx4 v[104:105], v[100:103], off offset:256
	v_lshl_add_u64 v[108:109], s[36:37], 0, v[96:97]
	s_waitcnt lgkmcnt(0)
	s_and_b64 vcc, exec, s[4:5]
	s_cbranch_vccnz .LBB5_681
	global_load_dwordx4 v[208:211], v255, s[38:39] offset:528
	global_load_dwordx4 v[212:215], v255, s[38:39] offset:512
	global_load_dwordx4 v[216:219], v255, s[40:41] offset:528
	global_load_dwordx4 v[220:223], v255, s[40:41] offset:512
	s_waitcnt vmcnt(12)
.LBB5_681:
	v_fmamk_f32 v96, v243, 0x3a800000, v189
	v_mul_f32_e32 v97, 0x4f800000, v96
	v_cmp_gt_f32_e32 vcc, s82, v96
	s_nop 1
	v_cndmask_b32_e32 v96, v96, v97, vcc
	v_sqrt_f32_e32 v97, v96
	s_nop 0
	v_add_u32_e32 v98, -1, v97
	v_fma_f32 v99, -v98, v97, v96
	v_cmp_ge_f32_e64 s[12:13], 0, v99
	v_add_u32_e32 v99, 1, v97
	s_nop 0
	v_cndmask_b32_e64 v98, v97, v98, s[12:13]
	v_fma_f32 v97, -v99, v97, v96
	v_cmp_lt_f32_e64 s[12:13], 0, v97
	s_nop 1
	v_cndmask_b32_e64 v97, v98, v99, s[12:13]
	v_mul_f32_e32 v98, 0x37800000, v97
	v_cndmask_b32_e32 v97, v97, v98, vcc
	v_cmp_class_f32_e32 vcc, v96, v190
	s_nop 1
	v_cndmask_b32_e32 v96, v97, v96, vcc
	v_div_scale_f32 v97, s[12:13], v96, v96, 1.0
	v_rcp_f32_e32 v98, v97
	s_nop 0
	v_fma_f32 v99, -v97, v98, 1.0
	v_fmac_f32_e32 v98, v99, v98
	v_div_scale_f32 v99, vcc, 1.0, v96, 1.0
	v_mul_f32_e32 v100, v99, v98
	v_fma_f32 v101, -v97, v100, v99
	v_fmac_f32_e32 v100, v101, v98
	v_fma_f32 v97, -v97, v100, v99
	v_div_fmas_f32 v97, v97, v98, v100
	v_div_fixup_f32 v96, v97, v96, 1.0
	v_mul_f32_e32 v97, 0x3e38aa3b, v96
	v_cndmask_b32_e64 v96, v96, v97, s[6:7]
	v_pk_mul_f32 v[94:95], v[94:95], v[96:97] op_sel_hi:[1,0]
	v_pk_mul_f32 v[92:93], v[92:93], v[96:97] op_sel_hi:[1,0]
	v_pk_mul_f32 v[90:91], v[90:91], v[96:97] op_sel_hi:[1,0]
	s_and_b64 vcc, exec, s[4:5]
	v_pk_mul_f32 v[98:99], v[88:89], v[96:97] op_sel_hi:[1,0]
	s_cbranch_vccnz .LBB5_685
	ds_bpermute_b32 v100, v185, v92
	ds_bpermute_b32 v88, v185, v98
	ds_bpermute_b32 v101, v185, v93
	ds_bpermute_b32 v89, v185, v99
	ds_bpermute_b32 v104, v185, v94
	ds_bpermute_b32 v103, v185, v90
	ds_bpermute_b32 v102, v185, v95
	ds_bpermute_b32 v97, v185, v91
	s_and_saveexec_b64 s[12:13], s[0:1]
	s_cbranch_execz .LBB5_684
	s_waitcnt lgkmcnt(2)
	v_mul_f32_e32 v103, v170, v103
	v_mul_f32_e32 v106, v42, v103
	s_waitcnt lgkmcnt(1)
	v_mul_f32_e32 v103, v170, v102
	v_mov_b32_e32 v108, v95
	v_mov_b32_e32 v109, v47
	v_mov_b32_e32 v102, v39
	v_pk_mul_f32 v[92:93], v[92:93], v[36:37]
	v_pk_mul_f32 v[100:101], v[170:171], v[100:101]
	v_pk_mul_f32 v[102:103], v[108:109], v[102:103]
	v_pk_fma_f32 v[92:93], v[44:45], v[100:101], v[92:93]
	v_mov_b32_e32 v95, v102
	v_mov_b32_e32 v105, v103
	s_waitcnt lgkmcnt(0)
	v_mul_f32_e32 v101, v170, v97
	v_mov_b32_e32 v102, v91
	v_mov_b32_e32 v103, v43
	v_mov_b32_e32 v100, v35
	v_mul_f32_e32 v104, v170, v104
	v_pk_mul_f32 v[100:101], v[102:103], v[100:101]
	v_pk_mul_f32 v[98:99], v[98:99], v[32:33]
	v_pk_mul_f32 v[88:89], v[170:171], v[88:89]
	v_mul_f32_e32 v94, v94, v38
	v_mul_f32_e32 v104, v46, v104
	v_mul_f32_e32 v90, v90, v34
	v_mov_b32_e32 v91, v100
	v_mov_b32_e32 v107, v101
	v_pk_add_f32 v[94:95], v[94:95], v[104:105]
	v_pk_fma_f32 v[98:99], v[40:41], v[88:89], v[98:99]
	v_pk_add_f32 v[90:91], v[90:91], v[106:107]

.LBB5_693:
	s_waitcnt lgkmcnt(2)
	v_add_u32_e32 v96, 0x80, v180
	v_ashrrev_i32_e32 v97, 31, v96
	v_cvt_pk_bf16_f32 v84, v84, v85
	v_cvt_pk_bf16_f32 v85, v86, v87
	v_cvt_pk_bf16_f32 v86, v80, v81
	v_lshlrev_b64 v[80:81], 6, v[96:97]
	v_cvt_pk_bf16_f32 v87, v82, v83
	global_store_dwordx4 v[88:89], v[84:87], off offset:256
	v_lshl_add_u64 v[92:93], s[36:37], 0, v[80:81]
	s_waitcnt lgkmcnt(0)
	s_and_b64 vcc, exec, s[4:5]
	s_cbranch_vccnz .LBB5_695
	global_load_dwordx4 v[32:35], v255, s[38:39] offset:1040
	global_load_dwordx4 v[36:39], v255, s[38:39] offset:1024
	global_load_dwordx4 v[40:43], v255, s[40:41] offset:1040
	global_load_dwordx4 v[44:47], v255, s[40:41] offset:1024
	s_waitcnt vmcnt(12)
.LBB5_695:
	v_fmamk_f32 v80, v244, 0x3a800000, v189
	v_mul_f32_e32 v81, 0x4f800000, v80
	v_cmp_gt_f32_e32 vcc, s82, v80
	s_nop 1
	v_cndmask_b32_e32 v80, v80, v81, vcc
	v_sqrt_f32_e32 v81, v80
	s_nop 0
	v_add_u32_e32 v82, -1, v81
	v_fma_f32 v83, -v82, v81, v80
	v_cmp_ge_f32_e64 s[12:13], 0, v83
	v_add_u32_e32 v83, 1, v81
	s_nop 0
	v_cndmask_b32_e64 v82, v81, v82, s[12:13]
	v_fma_f32 v81, -v83, v81, v80
	v_cmp_lt_f32_e64 s[12:13], 0, v81
	s_nop 1
	v_cndmask_b32_e64 v81, v82, v83, s[12:13]
	v_mul_f32_e32 v82, 0x37800000, v81
	v_cndmask_b32_e32 v81, v81, v82, vcc
	v_cmp_class_f32_e32 vcc, v80, v190
	s_nop 1
	v_cndmask_b32_e32 v80, v81, v80, vcc
	v_div_scale_f32 v81, s[12:13], v80, v80, 1.0
	v_rcp_f32_e32 v82, v81
	s_nop 0
	v_fma_f32 v83, -v81, v82, 1.0
	v_fmac_f32_e32 v82, v83, v82
	v_div_scale_f32 v83, vcc, 1.0, v80, 1.0
	v_mul_f32_e32 v84, v83, v82
	v_fma_f32 v85, -v81, v84, v83
	v_fmac_f32_e32 v84, v85, v82
	v_fma_f32 v81, -v81, v84, v83
	v_div_fmas_f32 v81, v81, v82, v84
	v_div_fixup_f32 v80, v81, v80, 1.0
	v_mul_f32_e32 v81, 0x3e38aa3b, v80
	v_cndmask_b32_e64 v80, v80, v81, s[6:7]
	v_pk_mul_f32 v[78:79], v[78:79], v[80:81] op_sel_hi:[1,0]
	v_pk_mul_f32 v[76:77], v[76:77], v[80:81] op_sel_hi:[1,0]
	v_pk_mul_f32 v[74:75], v[74:75], v[80:81] op_sel_hi:[1,0]
	s_and_b64 vcc, exec, s[4:5]
	v_pk_mul_f32 v[82:83], v[72:73], v[80:81] op_sel_hi:[1,0]
	s_cbranch_vccnz .LBB5_699
	ds_bpermute_b32 v84, v185, v76
	ds_bpermute_b32 v72, v185, v82
	ds_bpermute_b32 v85, v185, v77
	ds_bpermute_b32 v73, v185, v83
	ds_bpermute_b32 v88, v185, v78
	ds_bpermute_b32 v87, v185, v74
	ds_bpermute_b32 v86, v185, v79
	ds_bpermute_b32 v81, v185, v75
	s_and_saveexec_b64 s[12:13], s[0:1]
	s_cbranch_execz .LBB5_698
	s_waitcnt lgkmcnt(2)
	v_mul_f32_e32 v87, v170, v87
	v_mul_f32_e32 v90, v202, v87
	s_waitcnt lgkmcnt(1)
	v_mul_f32_e32 v87, v170, v86
	v_mov_b32_e32 v92, v79
	v_mov_b32_e32 v93, v207
	v_mov_b32_e32 v86, v199
	v_pk_mul_f32 v[76:77], v[76:77], v[196:197]
	v_pk_mul_f32 v[84:85], v[170:171], v[84:85]
	v_pk_mul_f32 v[86:87], v[92:93], v[86:87]
	v_pk_fma_f32 v[76:77], v[204:205], v[84:85], v[76:77]
	v_mov_b32_e32 v79, v86
	v_mov_b32_e32 v89, v87
	s_waitcnt lgkmcnt(0)
	v_mul_f32_e32 v85, v170, v81
	v_mov_b32_e32 v86, v75
	v_mov_b32_e32 v87, v203
	v_mov_b32_e32 v84, v195
	v_mul_f32_e32 v88, v170, v88
	v_pk_mul_f32 v[84:85], v[86:87], v[84:85]
	v_pk_mul_f32 v[82:83], v[82:83], v[192:193]
	v_pk_mul_f32 v[72:73], v[170:171], v[72:73]
	v_mul_f32_e32 v78, v78, v198
	v_mul_f32_e32 v88, v206, v88
	v_mul_f32_e32 v74, v74, v194
	v_mov_b32_e32 v75, v84
	v_mov_b32_e32 v91, v85
	v_pk_add_f32 v[78:79], v[78:79], v[88:89]
	v_pk_fma_f32 v[82:83], v[200:201], v[72:73], v[82:83]
	v_pk_add_f32 v[74:75], v[74:75], v[90:91]

.LBB5_701:
	s_waitcnt lgkmcnt(0)
	v_mov_b32_e32 v81, v80
	v_lshlrev_b64 v[72:73], 11, v[96:97]
	v_cvt_pk_bf16_f32 v76, v76, v77
	v_cvt_pk_bf16_f32 v77, v78, v79
	v_cvt_pk_bf16_f32 v78, v82, v83
	v_cvt_pk_bf16_f32 v79, v74, v75
	v_mov_b32_e32 v74, v80
	v_mov_b32_e32 v75, v80
	v_lshl_add_u64 v[72:73], v[144:145], 0, v[72:73]
	v_pk_mul_f32 v[70:71], v[70:71], v[74:75]
	v_pk_mul_f32 v[68:69], v[68:69], v[80:81]
	v_pk_mul_f32 v[66:67], v[66:67], v[74:75]
	s_and_b64 vcc, exec, s[4:5]
	v_pk_mul_f32 v[64:65], v[64:65], v[80:81]
	global_store_dwordx4 v[72:73], v[76:79], off
	s_cbranch_vccnz .LBB5_705
	ds_bpermute_b32 v76, v185, v68
	ds_bpermute_b32 v74, v185, v64
	ds_bpermute_b32 v77, v185, v69
	ds_bpermute_b32 v75, v185, v65
	ds_bpermute_b32 v81, v185, v70
	ds_bpermute_b32 v80, v185, v66
	ds_bpermute_b32 v79, v185, v71
	ds_bpermute_b32 v78, v185, v67
	s_and_saveexec_b64 s[12:13], s[0:1]
	s_cbranch_execz .LBB5_704
	v_pk_mul_f32 v[68:69], v[68:69], v[196:197]
	s_waitcnt lgkmcnt(5)
	v_pk_mul_f32 v[76:77], v[170:171], v[76:77]
	s_waitcnt lgkmcnt(1)
	v_mul_f32_e32 v85, v170, v79
	v_mov_b32_e32 v86, v71
	v_mov_b32_e32 v87, v207
	v_mov_b32_e32 v84, v199
	v_pk_fma_f32 v[68:69], v[204:205], v[76:77], v[68:69]
	s_waitcnt lgkmcnt(0)
	v_mul_f32_e32 v77, v170, v78
	v_mov_b32_e32 v78, v67
	v_mov_b32_e32 v79, v203
	v_mov_b32_e32 v76, v195
	v_mul_f32_e32 v81, v170, v81
	v_mul_f32_e32 v80, v170, v80
	v_pk_mul_f32 v[84:85], v[86:87], v[84:85]
	v_pk_mul_f32 v[76:77], v[78:79], v[76:77]
	v_pk_mul_f32 v[64:65], v[64:65], v[192:193]
	v_pk_mul_f32 v[74:75], v[170:171], v[74:75]
	v_mul_f32_e32 v70, v70, v198
	v_mul_f32_e32 v82, v206, v81
	v_mul_f32_e32 v66, v66, v194
	v_mul_f32_e32 v80, v202, v80
	v_mov_b32_e32 v71, v84
	v_mov_b32_e32 v83, v85
	v_mov_b32_e32 v67, v76
	v_mov_b32_e32 v81, v77
	v_pk_add_f32 v[70:71], v[70:71], v[82:83]
	v_pk_fma_f32 v[64:65], v[200:201], v[74:75], v[64:65]
	v_pk_add_f32 v[66:67], v[66:67], v[80:81]

.LBB5_707:
	s_waitcnt lgkmcnt(2)
	v_add_u32_e32 v80, 0x90, v180
	v_ashrrev_i32_e32 v81, 31, v80
	v_cvt_pk_bf16_f32 v68, v68, v69
	v_cvt_pk_bf16_f32 v69, v70, v71
	v_cvt_pk_bf16_f32 v70, v64, v65
	v_lshlrev_b64 v[64:65], 6, v[80:81]
	v_cvt_pk_bf16_f32 v71, v66, v67
	global_store_dwordx4 v[72:73], v[68:71], off offset:256
	v_lshl_add_u64 v[76:77], s[36:37], 0, v[64:65]
	s_waitcnt lgkmcnt(0)
	s_and_b64 vcc, exec, s[4:5]
	s_cbranch_vccnz .LBB5_709
	global_load_dwordx4 v[192:195], v255, s[38:39] offset:1552
	global_load_dwordx4 v[196:199], v255, s[38:39] offset:1536
	global_load_dwordx4 v[200:203], v255, s[40:41] offset:1552
	global_load_dwordx4 v[204:207], v255, s[40:41] offset:1536
	s_waitcnt vmcnt(12)
.LBB5_709:
	v_fmamk_f32 v64, v245, 0x3a800000, v189
	v_mul_f32_e32 v65, 0x4f800000, v64
	v_cmp_gt_f32_e32 vcc, s82, v64
	s_nop 1
	v_cndmask_b32_e32 v64, v64, v65, vcc
	v_sqrt_f32_e32 v65, v64
	s_nop 0
	v_add_u32_e32 v66, -1, v65
	v_fma_f32 v67, -v66, v65, v64
	v_cmp_ge_f32_e64 s[12:13], 0, v67
	v_add_u32_e32 v67, 1, v65
	s_nop 0
	v_cndmask_b32_e64 v66, v65, v66, s[12:13]
	v_fma_f32 v65, -v67, v65, v64
	v_cmp_lt_f32_e64 s[12:13], 0, v65
	s_nop 1
	v_cndmask_b32_e64 v65, v66, v67, s[12:13]
	v_mul_f32_e32 v66, 0x37800000, v65
	v_cndmask_b32_e32 v65, v65, v66, vcc
	v_cmp_class_f32_e32 vcc, v64, v190
	s_nop 1
	v_cndmask_b32_e32 v64, v65, v64, vcc
	v_div_scale_f32 v65, s[12:13], v64, v64, 1.0
	v_rcp_f32_e32 v66, v65
	s_nop 0
	v_fma_f32 v67, -v65, v66, 1.0
	v_fmac_f32_e32 v66, v67, v66
	v_div_scale_f32 v67, vcc, 1.0, v64, 1.0
	v_mul_f32_e32 v68, v67, v66
	v_fma_f32 v69, -v65, v68, v67
	v_fmac_f32_e32 v68, v69, v66
	v_fma_f32 v65, -v65, v68, v67
	v_div_fmas_f32 v65, v65, v66, v68
	v_div_fixup_f32 v64, v65, v64, 1.0
	v_mul_f32_e32 v65, 0x3e38aa3b, v64
	v_cndmask_b32_e64 v64, v64, v65, s[6:7]
	v_pk_mul_f32 v[62:63], v[62:63], v[64:65] op_sel_hi:[1,0]
	v_pk_mul_f32 v[60:61], v[60:61], v[64:65] op_sel_hi:[1,0]
	v_pk_mul_f32 v[58:59], v[58:59], v[64:65] op_sel_hi:[1,0]
	s_and_b64 vcc, exec, s[4:5]
	v_pk_mul_f32 v[66:67], v[56:57], v[64:65] op_sel_hi:[1,0]
	s_cbranch_vccnz .LBB5_713
	ds_bpermute_b32 v68, v185, v60
	ds_bpermute_b32 v56, v185, v66
	ds_bpermute_b32 v69, v185, v61
	ds_bpermute_b32 v57, v185, v67
	ds_bpermute_b32 v72, v185, v62
	ds_bpermute_b32 v71, v185, v58
	ds_bpermute_b32 v70, v185, v63
	ds_bpermute_b32 v65, v185, v59
	s_and_saveexec_b64 s[12:13], s[0:1]
	s_cbranch_execz .LBB5_712
	s_waitcnt lgkmcnt(2)
	v_mul_f32_e32 v71, v170, v71
	v_mul_f32_e32 v74, v218, v71
	s_waitcnt lgkmcnt(1)
	v_mul_f32_e32 v71, v170, v70
	v_mov_b32_e32 v76, v63
	v_mov_b32_e32 v77, v223
	v_mov_b32_e32 v70, v215
	v_pk_mul_f32 v[60:61], v[60:61], v[212:213]
	v_pk_mul_f32 v[68:69], v[170:171], v[68:69]
	v_pk_mul_f32 v[70:71], v[76:77], v[70:71]
	v_pk_fma_f32 v[60:61], v[220:221], v[68:69], v[60:61]
	v_mov_b32_e32 v63, v70
	v_mov_b32_e32 v73, v71
	s_waitcnt lgkmcnt(0)
	v_mul_f32_e32 v69, v170, v65
	v_mov_b32_e32 v70, v59
	v_mov_b32_e32 v71, v219
	v_mov_b32_e32 v68, v211
	v_mul_f32_e32 v72, v170, v72
	v_pk_mul_f32 v[68:69], v[70:71], v[68:69]
	v_pk_mul_f32 v[66:67], v[66:67], v[208:209]
	v_pk_mul_f32 v[56:57], v[170:171], v[56:57]
	v_mul_f32_e32 v62, v62, v214
	v_mul_f32_e32 v72, v222, v72
	v_mul_f32_e32 v58, v58, v210
	v_mov_b32_e32 v59, v68
	v_mov_b32_e32 v75, v69
	v_pk_add_f32 v[62:63], v[62:63], v[72:73]
	v_pk_fma_f32 v[66:67], v[216:217], v[56:57], v[66:67]
	v_pk_add_f32 v[58:59], v[58:59], v[74:75]

.LBB5_715:
	s_waitcnt lgkmcnt(0)
	v_mov_b32_e32 v65, v64
	v_lshlrev_b64 v[56:57], 11, v[80:81]
	v_cvt_pk_bf16_f32 v60, v60, v61
	v_cvt_pk_bf16_f32 v61, v62, v63
	v_cvt_pk_bf16_f32 v62, v66, v67
	v_cvt_pk_bf16_f32 v63, v58, v59
	v_mov_b32_e32 v58, v64
	v_mov_b32_e32 v59, v64
	v_lshl_add_u64 v[56:57], v[144:145], 0, v[56:57]
	v_pk_mul_f32 v[54:55], v[54:55], v[58:59]
	v_pk_mul_f32 v[52:53], v[52:53], v[64:65]
	v_pk_mul_f32 v[50:51], v[50:51], v[58:59]
	s_and_b64 vcc, exec, s[4:5]
	v_pk_mul_f32 v[48:49], v[48:49], v[64:65]
	global_store_dwordx4 v[56:57], v[60:63], off
	s_cbranch_vccnz .LBB5_719
	ds_bpermute_b32 v60, v185, v52
	ds_bpermute_b32 v58, v185, v48
	ds_bpermute_b32 v61, v185, v53
	ds_bpermute_b32 v59, v185, v49
	ds_bpermute_b32 v65, v185, v54
	ds_bpermute_b32 v64, v185, v50
	ds_bpermute_b32 v63, v185, v55
	ds_bpermute_b32 v62, v185, v51
	s_and_saveexec_b64 s[12:13], s[0:1]
	s_cbranch_execz .LBB5_718
	v_pk_mul_f32 v[52:53], v[52:53], v[212:213]
	s_waitcnt lgkmcnt(5)
	v_pk_mul_f32 v[60:61], v[170:171], v[60:61]
	s_waitcnt lgkmcnt(1)
	v_mul_f32_e32 v69, v170, v63
	v_mov_b32_e32 v70, v55
	v_mov_b32_e32 v71, v223
	v_mov_b32_e32 v68, v215
	v_pk_fma_f32 v[52:53], v[220:221], v[60:61], v[52:53]
	s_waitcnt lgkmcnt(0)
	v_mul_f32_e32 v61, v170, v62
	v_mov_b32_e32 v62, v51
	v_mov_b32_e32 v63, v219
	v_mov_b32_e32 v60, v211
	v_mul_f32_e32 v65, v170, v65
	v_mul_f32_e32 v64, v170, v64
	v_pk_mul_f32 v[68:69], v[70:71], v[68:69]
	v_pk_mul_f32 v[60:61], v[62:63], v[60:61]
	v_pk_mul_f32 v[48:49], v[48:49], v[208:209]
	v_pk_mul_f32 v[58:59], v[170:171], v[58:59]
	v_mul_f32_e32 v54, v54, v214
	v_mul_f32_e32 v66, v222, v65
	v_mul_f32_e32 v50, v50, v210
	v_mul_f32_e32 v64, v218, v64
	v_mov_b32_e32 v55, v68
	v_mov_b32_e32 v67, v69
	v_mov_b32_e32 v51, v60
	v_mov_b32_e32 v65, v61
	v_pk_add_f32 v[54:55], v[54:55], v[66:67]
	v_pk_fma_f32 v[48:49], v[216:217], v[58:59], v[48:49]
	v_pk_add_f32 v[50:51], v[50:51], v[64:65]

.LBB5_721:
	s_waitcnt lgkmcnt(2)
	v_add_u32_e32 v64, 0xa0, v180
	v_ashrrev_i32_e32 v65, 31, v64
	v_cvt_pk_bf16_f32 v52, v52, v53
	v_cvt_pk_bf16_f32 v53, v54, v55
	v_cvt_pk_bf16_f32 v54, v48, v49
	v_lshlrev_b64 v[48:49], 6, v[64:65]
	v_cvt_pk_bf16_f32 v55, v50, v51
	global_store_dwordx4 v[56:57], v[52:55], off offset:256
	v_lshl_add_u64 v[60:61], s[36:37], 0, v[48:49]
	s_waitcnt lgkmcnt(0)
	s_and_b64 vcc, exec, s[4:5]
	s_cbranch_vccnz .LBB5_723
	s_waitcnt vmcnt(8)
.LBB5_723:
	v_fmamk_f32 v48, v246, 0x3a800000, v189
	v_mul_f32_e32 v49, 0x4f800000, v48
	v_cmp_gt_f32_e32 vcc, s82, v48
	s_nop 1
	v_cndmask_b32_e32 v48, v48, v49, vcc
	v_sqrt_f32_e32 v49, v48
	s_nop 0
	v_add_u32_e32 v50, -1, v49
	v_fma_f32 v51, -v50, v49, v48
	v_cmp_ge_f32_e64 s[12:13], 0, v51
	v_add_u32_e32 v51, 1, v49
	s_nop 0
	v_cndmask_b32_e64 v50, v49, v50, s[12:13]
	v_fma_f32 v49, -v51, v49, v48
	v_cmp_lt_f32_e64 s[12:13], 0, v49
	s_nop 1
	v_cndmask_b32_e64 v49, v50, v51, s[12:13]
	v_mul_f32_e32 v50, 0x37800000, v49
	v_cndmask_b32_e32 v49, v49, v50, vcc
	v_cmp_class_f32_e32 vcc, v48, v190
	s_nop 1
	v_cndmask_b32_e32 v48, v49, v48, vcc
	v_div_scale_f32 v49, s[12:13], v48, v48, 1.0
	v_rcp_f32_e32 v50, v49
	s_nop 0
	v_fma_f32 v51, -v49, v50, 1.0
	v_fmac_f32_e32 v50, v51, v50
	v_div_scale_f32 v51, vcc, 1.0, v48, 1.0
	v_mul_f32_e32 v52, v51, v50
	v_fma_f32 v53, -v49, v52, v51
	v_fmac_f32_e32 v52, v53, v50
	v_fma_f32 v49, -v49, v52, v51
	v_div_fmas_f32 v49, v49, v50, v52
	v_div_fixup_f32 v48, v49, v48, 1.0
	v_mul_f32_e32 v49, 0x3e38aa3b, v48
	v_cndmask_b32_e64 v48, v48, v49, s[6:7]
	v_pk_mul_f32 v[30:31], v[30:31], v[48:49] op_sel_hi:[1,0]
	v_pk_mul_f32 v[28:29], v[28:29], v[48:49] op_sel_hi:[1,0]
	v_pk_mul_f32 v[26:27], v[26:27], v[48:49] op_sel_hi:[1,0]
	s_and_b64 vcc, exec, s[4:5]
	v_pk_mul_f32 v[50:51], v[24:25], v[48:49] op_sel_hi:[1,0]
	s_cbranch_vccnz .LBB5_727
	ds_bpermute_b32 v52, v185, v28
	ds_bpermute_b32 v24, v185, v50
	ds_bpermute_b32 v53, v185, v29
	ds_bpermute_b32 v25, v185, v51
	ds_bpermute_b32 v56, v185, v30
	ds_bpermute_b32 v55, v185, v26
	ds_bpermute_b32 v54, v185, v31
	ds_bpermute_b32 v49, v185, v27
	s_and_saveexec_b64 s[12:13], s[0:1]
	s_cbranch_execz .LBB5_726
	s_waitcnt lgkmcnt(2)
	v_mul_f32_e32 v55, v170, v55
	v_mul_f32_e32 v58, v42, v55
	s_waitcnt lgkmcnt(1)
	v_mul_f32_e32 v55, v170, v54
	v_mov_b32_e32 v60, v31
	v_mov_b32_e32 v61, v47
	v_mov_b32_e32 v54, v39
	v_pk_mul_f32 v[28:29], v[28:29], v[36:37]
	v_pk_mul_f32 v[52:53], v[170:171], v[52:53]
	v_pk_mul_f32 v[54:55], v[60:61], v[54:55]
	v_pk_fma_f32 v[28:29], v[44:45], v[52:53], v[28:29]
	v_mov_b32_e32 v31, v54
	v_mov_b32_e32 v57, v55
	s_waitcnt lgkmcnt(0)
	v_mul_f32_e32 v53, v170, v49
	v_mov_b32_e32 v54, v27
	v_mov_b32_e32 v55, v43
	v_mov_b32_e32 v52, v35
	v_mul_f32_e32 v56, v170, v56
	v_pk_mul_f32 v[52:53], v[54:55], v[52:53]
	v_pk_mul_f32 v[50:51], v[50:51], v[32:33]
	v_pk_mul_f32 v[24:25], v[170:171], v[24:25]
	v_mul_f32_e32 v30, v30, v38
	v_mul_f32_e32 v56, v46, v56
	v_mul_f32_e32 v26, v26, v34
	v_mov_b32_e32 v27, v52
	v_mov_b32_e32 v59, v53
	v_pk_add_f32 v[30:31], v[30:31], v[56:57]
	v_pk_fma_f32 v[50:51], v[40:41], v[24:25], v[50:51]
	v_pk_add_f32 v[26:27], v[26:27], v[58:59]

.LBB5_735:
	s_waitcnt lgkmcnt(2)
	v_add_u32_e32 v48, 0xb0, v180
	v_ashrrev_i32_e32 v49, 31, v48
	v_cvt_pk_bf16_f32 v20, v20, v21
	v_cvt_pk_bf16_f32 v21, v22, v23
	v_cvt_pk_bf16_f32 v22, v16, v17
	v_lshlrev_b64 v[16:17], 6, v[48:49]
	v_cvt_pk_bf16_f32 v23, v18, v19
	global_store_dwordx4 v[24:25], v[20:23], off offset:256
	v_lshl_add_u64 v[28:29], s[36:37], 0, v[16:17]
	s_waitcnt lgkmcnt(0)
	s_and_b64 vcc, exec, s[4:5]
	s_cbranch_vccnz .LBB5_737
	s_waitcnt vmcnt(4)
.LBB5_737:
	v_fmamk_f32 v16, v247, 0x3a800000, v189
	v_mul_f32_e32 v17, 0x4f800000, v16
	v_cmp_gt_f32_e32 vcc, s82, v16
	s_nop 1
	v_cndmask_b32_e32 v16, v16, v17, vcc
	v_sqrt_f32_e32 v17, v16
	s_nop 0
	v_add_u32_e32 v18, -1, v17
	v_fma_f32 v19, -v18, v17, v16
	v_cmp_ge_f32_e64 s[12:13], 0, v19
	v_add_u32_e32 v19, 1, v17
	s_nop 0
	v_cndmask_b32_e64 v18, v17, v18, s[12:13]
	v_fma_f32 v17, -v19, v17, v16
	v_cmp_lt_f32_e64 s[12:13], 0, v17
	s_nop 1
	v_cndmask_b32_e64 v17, v18, v19, s[12:13]
	v_mul_f32_e32 v18, 0x37800000, v17
	v_cndmask_b32_e32 v17, v17, v18, vcc
	v_cmp_class_f32_e32 vcc, v16, v190
	s_nop 1
	v_cndmask_b32_e32 v16, v17, v16, vcc
	v_div_scale_f32 v17, s[12:13], v16, v16, 1.0
	v_rcp_f32_e32 v18, v17
	s_nop 0
	v_fma_f32 v19, -v17, v18, 1.0
	v_fmac_f32_e32 v18, v19, v18
	v_div_scale_f32 v19, vcc, 1.0, v16, 1.0
	v_mul_f32_e32 v20, v19, v18
	v_fma_f32 v21, -v17, v20, v19
	v_fmac_f32_e32 v20, v21, v18
	v_fma_f32 v17, -v17, v20, v19
	v_div_fmas_f32 v17, v17, v18, v20
	v_div_fixup_f32 v16, v17, v16, 1.0
	v_mul_f32_e32 v17, 0x3e38aa3b, v16
	v_cndmask_b32_e64 v16, v16, v17, s[6:7]
	v_pk_mul_f32 v[14:15], v[14:15], v[16:17] op_sel_hi:[1,0]
	v_pk_mul_f32 v[12:13], v[12:13], v[16:17] op_sel_hi:[1,0]
	v_pk_mul_f32 v[10:11], v[10:11], v[16:17] op_sel_hi:[1,0]
	s_and_b64 vcc, exec, s[4:5]
	v_pk_mul_f32 v[18:19], v[8:9], v[16:17] op_sel_hi:[1,0]
	s_cbranch_vccnz .LBB5_741
	ds_bpermute_b32 v20, v185, v12
	ds_bpermute_b32 v8, v185, v18
	ds_bpermute_b32 v21, v185, v13
	ds_bpermute_b32 v9, v185, v19
	ds_bpermute_b32 v24, v185, v14
	ds_bpermute_b32 v23, v185, v10
	ds_bpermute_b32 v22, v185, v15
	ds_bpermute_b32 v17, v185, v11
	s_and_saveexec_b64 s[6:7], s[0:1]
	s_cbranch_execz .LBB5_740
	s_waitcnt lgkmcnt(2)
	v_mul_f32_e32 v23, v170, v23
	v_mul_f32_e32 v26, v202, v23
	s_waitcnt lgkmcnt(1)
	v_mul_f32_e32 v23, v170, v22
	v_mov_b32_e32 v28, v15
	v_mov_b32_e32 v29, v207
	v_mov_b32_e32 v22, v199
	v_pk_mul_f32 v[12:13], v[12:13], v[196:197]
	v_pk_mul_f32 v[20:21], v[170:171], v[20:21]
	v_pk_mul_f32 v[22:23], v[28:29], v[22:23]
	v_pk_fma_f32 v[12:13], v[204:205], v[20:21], v[12:13]
	v_mov_b32_e32 v15, v22
	v_mov_b32_e32 v25, v23
	s_waitcnt lgkmcnt(0)
	v_mul_f32_e32 v21, v170, v17
	v_mov_b32_e32 v22, v11
	v_mov_b32_e32 v23, v203
	v_mov_b32_e32 v20, v195
	v_mul_f32_e32 v24, v170, v24
	v_pk_mul_f32 v[20:21], v[22:23], v[20:21]
	v_pk_mul_f32 v[18:19], v[18:19], v[192:193]
	v_pk_mul_f32 v[8:9], v[170:171], v[8:9]
	v_mul_f32_e32 v14, v14, v198
	v_mul_f32_e32 v24, v206, v24
	v_mul_f32_e32 v10, v10, v194
	v_mov_b32_e32 v11, v20
	v_mov_b32_e32 v27, v21
	v_pk_add_f32 v[14:15], v[14:15], v[24:25]
	v_pk_fma_f32 v[18:19], v[200:201], v[8:9], v[18:19]
	v_pk_add_f32 v[10:11], v[10:11], v[26:27]

.LBB5_743:
	s_waitcnt lgkmcnt(0)
	v_mov_b32_e32 v17, v16
	v_lshlrev_b64 v[8:9], 11, v[48:49]
	v_cvt_pk_bf16_f32 v12, v12, v13
	v_cvt_pk_bf16_f32 v13, v14, v15
	v_cvt_pk_bf16_f32 v14, v18, v19
	v_cvt_pk_bf16_f32 v15, v10, v11
	v_mov_b32_e32 v10, v16
	v_mov_b32_e32 v11, v16
	v_lshl_add_u64 v[8:9], v[144:145], 0, v[8:9]
	v_pk_mul_f32 v[6:7], v[6:7], v[10:11]
	v_pk_mul_f32 v[4:5], v[4:5], v[16:17]
	v_pk_mul_f32 v[2:3], v[2:3], v[10:11]
	s_and_b64 vcc, exec, s[4:5]
	v_pk_mul_f32 v[0:1], v[0:1], v[16:17]
	global_store_dwordx4 v[8:9], v[12:15], off
	s_cbranch_vccnz .LBB5_747
	ds_bpermute_b32 v12, v185, v4
	ds_bpermute_b32 v10, v185, v0
	ds_bpermute_b32 v13, v185, v5
	ds_bpermute_b32 v11, v185, v1
	ds_bpermute_b32 v17, v185, v6
	ds_bpermute_b32 v16, v185, v2
	ds_bpermute_b32 v15, v185, v7
	ds_bpermute_b32 v14, v185, v3
	s_and_saveexec_b64 s[4:5], s[0:1]
	s_cbranch_execz .LBB5_746
	v_pk_mul_f32 v[4:5], v[4:5], v[196:197]
	s_waitcnt lgkmcnt(5)
	v_pk_mul_f32 v[12:13], v[170:171], v[12:13]
	s_waitcnt lgkmcnt(3)
	v_mul_f32_e32 v17, v170, v17
	s_waitcnt lgkmcnt(2)
	v_mul_f32_e32 v16, v170, v16
	v_mul_f32_e32 v18, v206, v17
	v_mul_f32_e32 v16, v202, v16
	s_waitcnt lgkmcnt(1)
	v_mul_f32_e32 v21, v170, v15
	v_mov_b32_e32 v206, v7
	v_mov_b32_e32 v20, v199
	v_pk_fma_f32 v[4:5], v[204:205], v[12:13], v[4:5]
	s_waitcnt lgkmcnt(0)
	v_mul_f32_e32 v13, v170, v14
	v_mov_b32_e32 v202, v3
	v_mov_b32_e32 v12, v195
	v_pk_mul_f32 v[20:21], v[206:207], v[20:21]
	v_pk_mul_f32 v[12:13], v[202:203], v[12:13]
	v_pk_mul_f32 v[0:1], v[0:1], v[192:193]
	v_pk_mul_f32 v[10:11], v[170:171], v[10:11]
	v_mul_f32_e32 v6, v6, v198
	v_mul_f32_e32 v2, v2, v194
	v_mov_b32_e32 v7, v20
	v_mov_b32_e32 v19, v21
	v_mov_b32_e32 v3, v12
	v_mov_b32_e32 v17, v13
	v_pk_add_f32 v[6:7], v[6:7], v[18:19]
	v_pk_fma_f32 v[0:1], v[200:201], v[10:11], v[0:1]
	v_pk_add_f32 v[2:3], v[2:3], v[16:17]

.LBB5_753:
	s_nop 0
	s_nop 0
	s_nop 0
	s_cmp_gt_i32 s75, 6
	s_cselect_b64 s[0:1], -1, 0
	s_and_b64 s[4:5], s[14:15], s[0:1]
	s_and_b64 vcc, exec, s[4:5]
	s_cbranch_vccz .LBB5_803
	v_mbcnt_lo_u32_b32 v0, -1, 0
	v_readlane_b32 s3, v250, 0
	v_mbcnt_hi_u32_b32 v0, -1, v0
	s_waitcnt vmcnt(0)
	s_andn2_b32 s3, s3, 63
	v_sub_u32_e32 v0, 0, v0
	v_cmp_eq_u32_e32 vcc, s3, v0
	s_waitcnt lgkmcnt(0)
	s_barrier
	s_and_saveexec_b64 s[4:5], vcc
	s_cbranch_execz .LBB5_802
	v_mov_b32_e32 v0, s61
	s_waitcnt vmcnt(0) expcnt(0) lgkmcnt(0)
	ds_read_b32 v2, v0
	ds_read_b32 v0, v0 offset:4
	s_waitcnt lgkmcnt(1)
	v_cmp_ne_u32_e32 vcc, 0, v2
	s_cbranch_vccnz .LBB5_770
	v_readlane_b32 s6, v250, 1
	v_readlane_b32 s7, v250, 2
	s_load_dwordx2 s[10:11], s[6:7], 0x4
	s_add_u32 s6, s72, 0x4200
	s_addc_u32 s7, s73, 0
	s_add_u32 s8, s72, 0x4400
	s_addc_u32 s9, s73, 0
	s_waitcnt lgkmcnt(0)
	s_mul_i32 s3, s10, s90
	s_add_u32 s10, s72, 0x4500
	s_mul_i32 s3, s3, s11
	s_addc_u32 s11, s73, 0
	s_add_u32 s12, s72, 0x4600
	s_addc_u32 s13, s73, 0
	s_add_u32 s14, s72, 0x4700
	s_addc_u32 s15, s73, 0
	s_add_u32 s16, s72, 0x4800
	s_addc_u32 s17, s73, 0
	s_add_u32 s18, s72, 0x4900
	s_addc_u32 s19, s73, 0
	s_add_u32 s20, s72, 0x4a00
	s_addc_u32 s21, s73, 0
	s_add_u32 s22, s72, 0x4b00
	s_addc_u32 s23, s73, 0
	s_add_u32 s26, s72, 0x4c00
	s_addc_u32 s27, s73, 0
	s_add_u32 s36, s72, 0x4d00
	s_addc_u32 s37, s73, 0
	s_add_u32 s38, s72, 0x4e00
	s_addc_u32 s39, s73, 0
	s_add_u32 s40, s72, 0x4f00
	s_addc_u32 s41, s73, 0
	s_add_u32 s42, s72, 0x5000
	s_addc_u32 s43, s73, 0
	s_add_u32 s44, s72, 0x5100
	s_addc_u32 s45, s73, 0
	s_add_u32 s46, s72, 0x5200
	s_addc_u32 s47, s73, 0
	s_add_u32 s48, s72, 0x5300
	s_addc_u32 s49, s73, 0
	s_mov_b32 s24, 1
	v_mov_b32_e32 v16, 0
	s_branch .LBB5_758
